# FFN-down context K-slice units moved from the DN phase second round into the idle tail of the preceding FFN-up phase (WGs 150..193), up-projection context tiles reordered into round 0 and flag-release
# speedup vs baseline: 1.0295x; 1.0078x over previous
.Lcvth_done2:
.LBB0_156:
	s_movk_i32 s32, 0x207
	s_mov_b32 s0, 0
	v_writelane_b32 v255, s0, 46
	s_mov_b32 s0, 0
	v_writelane_b32 v255, s0, 47
	s_add_u32 s0, s62, 0x22f28000
	s_addc_u32 s1, s63, 0
	v_writelane_b32 v251, s0, 37
	s_waitcnt vmcnt(11)
	v_mbcnt_lo_u32_b32 v0, -1, 0
	s_mov_b32 s89, 1
	v_writelane_b32 v251, s1, 38
	s_add_u32 s0, s62, 0x22f30000
	s_addc_u32 s1, s63, 0
	v_writelane_b32 v251, s0, 39
	s_waitcnt lgkmcnt(0)
	s_movk_i32 s33, 0x3000
	v_mov_b32_e32 v33, 0
	v_writelane_b32 v251, s1, 40
	s_add_u32 s0, s62, 0x1bee0000
	v_writelane_b32 v251, s0, 41
	s_addc_u32 s0, s63, 0
	v_writelane_b32 v251, s0, 42
	s_add_u32 s0, s62, 0x22f38200
	s_addc_u32 s1, s63, 0
	s_add_u32 s2, s62, 0x22f38400
	s_addc_u32 s3, s63, 0
	s_add_u32 s4, s62, 0x22f38500
	s_addc_u32 s5, s63, 0
	s_add_u32 s6, s62, 0x22f38600
	v_writelane_b32 v251, s0, 43
	s_addc_u32 s7, s63, 0
	v_mov_b32_e32 v228, 0x1000
	v_writelane_b32 v251, s1, 44
	s_add_u32 s0, s62, 0x22f38700
	s_addc_u32 s1, s63, 0
	v_writelane_b32 v251, s0, 45
	v_mov_b32_e32 v221, 0x2000
	v_mov_b32_e32 v248, 1
	v_writelane_b32 v251, s1, 46
	s_add_u32 s0, s62, 0x22f38800
	s_addc_u32 s1, s63, 0
	v_writelane_b32 v251, s0, 47
	v_mov_b32_e32 v224, 0x358637bd
	v_mbcnt_hi_u32_b32 v220, -1, v0
	v_writelane_b32 v251, s1, 48
	s_add_u32 s0, s62, 0x22f38900
	s_addc_u32 s1, s63, 0
	v_writelane_b32 v251, s0, 49
	v_mov_b32_e32 v225, 0x42800000
	v_not_b32_e32 v226, 63
	v_writelane_b32 v251, s1, 50
	s_add_u32 s0, s62, 0x22f38a00
	s_addc_u32 s1, s63, 0
	v_writelane_b32 v251, s0, 51
	v_mov_b32_e32 v227, 0x410000
	v_mov_b32_e32 v249, 0x160000
	v_writelane_b32 v251, s1, 52
	s_add_u32 s0, s62, 0x22f38b00
	s_addc_u32 s1, s63, 0
	v_writelane_b32 v251, s0, 53
	s_mov_b32 s94, 0x8200
	s_mov_b32 s66, 0xc2fc0000
	v_writelane_b32 v251, s1, 54
	s_add_u32 s0, s62, 0x22f38c00
	s_addc_u32 s1, s63, 0
	v_writelane_b32 v251, s0, 55
	s_movk_i32 s67, 0xffc0
	s_movk_i32 s88, 0x1000
	v_writelane_b32 v251, s1, 56
	s_add_u32 s0, s62, 0x22f38d00
	s_addc_u32 s1, s63, 0
	v_writelane_b32 v251, s0, 57
	s_mov_b32 s78, 0
	s_mov_b32 s97, 0
	v_writelane_b32 v251, s1, 58
	s_add_u32 s0, s62, 0x22f38e00
	s_addc_u32 s1, s63, 0
	v_writelane_b32 v251, s0, 59
	s_mov_b64 s[34:35], 0x100000
	s_mov_b64 s[68:69], 0x100800
	v_writelane_b32 v251, s1, 60
	s_add_u32 s0, s62, 0x22f38f00
	s_addc_u32 s1, s63, 0
	v_writelane_b32 v251, s0, 61
	s_mov_b64 s[84:85], 0x80
	s_nop 0
	v_writelane_b32 v251, s1, 62
	s_add_u32 s0, s62, 0x22f39000
	s_addc_u32 s1, s63, 0
	v_writelane_b32 v251, s0, 63
	s_nop 1
	v_writelane_b32 v252, s1, 0
	s_add_u32 s0, s62, 0x22f39100
	s_addc_u32 s1, s63, 0
	v_writelane_b32 v252, s0, 1
	s_nop 1
	v_writelane_b32 v252, s1, 2
	s_add_u32 s0, s62, 0x22f39200
	s_addc_u32 s1, s63, 0
	v_writelane_b32 v252, s0, 3
	s_nop 1
	v_writelane_b32 v252, s1, 4
	s_add_u32 s0, s62, 0x22f39300
	s_addc_u32 s1, s63, 0
	v_writelane_b32 v252, s0, 5
	s_nop 1
	v_writelane_b32 v252, s1, 6
	s_add_u32 s0, s62, 0x22f3b400
	s_addc_u32 s1, s63, 0
	s_add_u32 s52, s62, 0x22f3b500
	v_writelane_b32 v252, s0, 7
	s_addc_u32 s53, s63, 0
	s_nop 0
	v_writelane_b32 v252, s1, 8
	s_add_u32 s0, s62, 0x2080000
	s_addc_u32 s1, s63, 0
	v_writelane_b32 v252, s0, 9
	s_nop 1
	v_writelane_b32 v252, s1, 10
	s_add_u32 s0, s62, 0x22f3c000
	s_addc_u32 s1, s63, 0
	s_add_u32 s70, s62, 0x9a60000
	v_writelane_b32 v252, s0, 11
	s_addc_u32 s71, s63, 0
	s_nop 0
	v_writelane_b32 v252, s1, 12
	s_add_u32 s0, s62, 0x8200000
	s_addc_u32 s1, s63, 0
	v_writelane_b32 v252, s0, 13
	s_nop 1
	v_writelane_b32 v252, s1, 14
	s_add_u32 s0, s62, 0x15d60000
	s_addc_u32 s1, s63, 0
	s_add_u32 s92, s62, 0x4100000
	v_writelane_b32 v252, s0, 15
	s_addc_u32 s93, s63, 0
	s_nop 0
	v_writelane_b32 v252, s1, 16
	s_add_u32 s0, s62, 0x19e60000
	s_addc_u32 s1, s63, 0
	v_writelane_b32 v252, s0, 17
	s_nop 1
	v_writelane_b32 v252, s1, 18
	s_add_u32 s0, s62, 0x17de0000
	s_addc_u32 s1, s63, 0
	v_writelane_b32 v252, s0, 19
	s_bitcmp1_b32 s91, 0
	s_nop 0
	v_writelane_b32 v252, s1, 20
	s_cselect_b64 s[0:1], -1, 0
	v_writelane_b32 v252, s0, 21
	s_nop 1
	v_writelane_b32 v252, s1, 22
	s_add_u32 s0, s62, 0x23a3c000
	v_writelane_b32 v252, s0, 23
	s_addc_u32 s0, s63, 0
	v_writelane_b32 v252, s0, 24
	s_add_u32 s0, s62, 0x23abc000
	v_writelane_b32 v252, s0, 25
	v_writelane_b32 v252, s56, 26
	s_addc_u32 s0, s63, 0
	s_add_i32 s80, 0, 0x11000
	v_writelane_b32 v252, s57, 27
	v_writelane_b32 v252, s58, 28
	v_writelane_b32 v252, s59, 29
	v_writelane_b32 v252, s60, 30
	v_writelane_b32 v252, s61, 31
	v_writelane_b32 v252, s62, 32
	v_writelane_b32 v252, s63, 33
	v_writelane_b32 v252, s0, 34
	s_add_i32 s0, 0, 0x23ff0
	v_writelane_b32 v252, s0, 35
	s_add_i32 s0, 0, 0x23ff4
	v_writelane_b32 v252, s0, 36
	s_add_i32 s0, 0, 0x22000
	v_writelane_b32 v252, s0, 37
	v_writelane_b32 v252, s52, 38
	s_mov_b64 s[56:57], s[2:3]
	s_mov_b64 s[58:59], s[4:5]
	v_writelane_b32 v252, s53, 39
	v_writelane_b32 v252, s56, 40
	s_mov_b64 s[60:61], s[6:7]
	s_add_i32 s81, 0, 0x19800
	v_writelane_b32 v252, s57, 41
	v_writelane_b32 v252, s58, 42
	s_nop 1
	v_writelane_b32 v252, s59, 43
	v_writelane_b32 v252, s60, 44
	s_nop 1
	v_writelane_b32 v252, s61, 45
	v_writelane_b32 v252, s91, 46
	v_writelane_b32 v252, s54, 47
	s_nop 1
	v_writelane_b32 v252, s55, 48
	v_writelane_b32 v252, s64, 49
	s_nop 1
	v_writelane_b32 v252, s65, 50

.LBB0_453:
	v_readlane_b32 s14, v252, 47
	v_readlane_b32 s15, v252, 48
	s_barrier
	v_readlane_b32 s3, v252, 46
	v_readlane_b32 s12, v255, 45
	s_cmp_lt_u32 s3, 162
	s_cbranch_scc1 .Lcvti_skip
	s_cmp_gt_u32 s12, 2
	s_cbranch_scc1 .Lcvti_skip
	s_add_i32 s12, s12, 1
	v_readlane_b32 s4, v251, 36
	s_sub_i32 s0, s3, 162
	s_lshl_b32 s0, s0, 3
	s_add_i32 s0, s0, s4
	s_mul_i32 s15, s4, 0x2100
	s_mov_b32 s1, 752
	s_movk_i32 s14, 10576
	s_add_i32 s0, s0, 3760

.Lcvti_done2:
.Lcvti_skip:
	v_readlane_b32 s14, v252, 47
	v_readlane_b32 s15, v252, 48

.LBB0_1261:
	v_readlane_b32 s0, v251, 36
	s_mov_b32 s22, s91
	v_readlane_b32 s4, v252, 47
	s_waitcnt vmcnt(0)
	v_lshl_add_u32 v8, s0, 6, v220
	s_and_b32 s0, s91, 63
	s_add_i32 s1, s0, -1
	s_cmp_lt_u32 s1, 5
	s_cbranch_scc0 .Lupr0_done
	s_sub_i32 s1, s91, s0
	s_lshl_b32 s0, s0, 8
	s_add_i32 s1, s1, s0
	s_cmpk_gt_i32 s1, 0x595
	s_cbranch_scc1 .Lupr0_done
	s_mov_b32 s22, s1
.Lupr0_done:
	s_cmpk_gt_i32 s22, 0x595
	v_readfirstlane_b32 s23, v8
	v_readlane_b32 s5, v252, 48
	s_cbranch_scc1 .LBB0_1281
	s_ashr_i32 s0, s22, 31
	s_lshr_b32 s0, s0, 29
	s_add_i32 s4, s22, s0
	s_and_b32 s0, s4, -8
	s_sub_i32 s2, s22, s0
	s_cmp_gt_i32 s2, 5
	s_mov_b64 s[0:1], -1
	s_cbranch_scc0 .LBB0_1264
	s_mul_i32 s0, s2, 0xb2
	s_add_i32 s3, s0, 6
	s_mov_b64 s[0:1], 0

.LBB0_1269:
	s_load_dword s0, s[64:65], 0x0
	s_add_i32 s34, s34, 1
	s_mov_b64 s[10:11], s[14:15]
	s_mov_b64 s[12:13], s[16:17]
	s_waitcnt lgkmcnt(0)
	s_mul_i32 s3, s34, s0
	s_add_i32 s3, s3, s91
	s_and_b32 s0, s91, 63
	s_cmp_lg_u32 s0, 0
	s_cbranch_scc1 .Lupr1_done
	s_cmp_gt_u32 s34, 5
	s_cbranch_scc1 .Lupr1_done
	s_cmpk_gt_i32 s3, 0x595
	s_cbranch_scc1 .Lupr1_done
	s_add_i32 s3, s91, s34
.Lupr1_done:
	s_cmpk_gt_i32 s3, 0x595
	s_cselect_b64 s[0:1], -1, 0
	s_and_b64 vcc, exec, s[0:1]
	s_cbranch_vccnz .LBB0_1275
	s_ashr_i32 s2, s3, 31
	s_lshr_b32 s2, s2, 29
	s_add_i32 s4, s3, s2
	s_and_b32 s2, s4, -8
	s_sub_i32 s5, s3, s2
	s_cmp_gt_i32 s5, 5
	s_mov_b64 s[2:3], -1
	s_cbranch_scc0 .LBB0_1272
	s_mul_i32 s2, s5, 0xb2
	s_add_i32 s6, s2, 6
	s_mov_b64 s[2:3], 0

.LBB0_1276:
	s_add_u32 s16, s14, 0x100
	s_addc_u32 s17, s15, 0
	s_add_i32 s39, 0, 0x10000
	v_add_u32_e32 v152, s39, v137
	ds_read_b128 v[140:143], v152
	ds_read_b128 v[144:147], v152 offset:1024
	ds_read_b128 v[148:151], v152 offset:2048
	ds_read_b128 v[152:155], v152 offset:3072
	s_cmp_eq_u32 s38, 12
	s_cselect_b32 s21, s11, s17
	s_cselect_b32 s20, s10, s16
	s_cselect_b32 s19, s13, s37
	s_cselect_b32 s18, s12, s3
	v_lshl_add_u64 v[188:189], s[14:15], 0, v[132:133]
	s_add_i32 m0, s9, 0xc000
	ds_read_b128 v[156:159], v139
	ds_read_b128 v[160:163], v139 offset:1024
	ds_read_b128 v[164:167], v139 offset:2048
	ds_read_b128 v[168:171], v139 offset:3072
	ds_read_b128 v[172:175], v139 offset:4096
	ds_read_b128 v[176:179], v139 offset:5120
	ds_read_b128 v[180:183], v139 offset:6144
	ds_read_b128 v[184:187], v139 offset:7168
	global_load_lds_dwordx4 v[188:189], off
	v_lshl_add_u64 v[188:189], s[14:15], 0, v[134:135]
	s_add_i32 m0, s9, 0xe000
	s_nop 0
	global_load_lds_dwordx4 v[188:189], off
	s_waitcnt lgkmcnt(8)
	s_barrier
	s_waitcnt lgkmcnt(0)
	s_setprio 1
	s_waitcnt lgkmcnt(0)
	v_mfma_f32_16x16x32_f16 v[126:129], v[140:143], v[156:159], v[126:129]
	v_mfma_f32_16x16x32_f16 v[122:125], v[148:151], v[156:159], v[122:125]
	v_mfma_f32_16x16x32_f16 v[110:113], v[140:143], v[164:167], v[110:113]
	v_mfma_f32_16x16x32_f16 v[106:109], v[148:151], v[164:167], v[106:109]
	v_mfma_f32_16x16x32_f16 v[94:97], v[140:143], v[172:175], v[94:97]
	v_mfma_f32_16x16x32_f16 v[90:93], v[148:151], v[172:175], v[90:93]
	v_mfma_f32_16x16x32_f16 v[78:81], v[140:143], v[180:183], v[78:81]
	v_mfma_f32_16x16x32_f16 v[74:77], v[148:151], v[180:183], v[74:77]
	v_mfma_f32_16x16x32_f16 v[126:129], v[144:147], v[160:163], v[126:129]
	v_mfma_f32_16x16x32_f16 v[122:125], v[152:155], v[160:163], v[122:125]
	v_mfma_f32_16x16x32_f16 v[110:113], v[144:147], v[168:171], v[110:113]
	v_mfma_f32_16x16x32_f16 v[106:109], v[152:155], v[168:171], v[106:109]
	v_mfma_f32_16x16x32_f16 v[94:97], v[144:147], v[176:179], v[94:97]
	v_mfma_f32_16x16x32_f16 v[90:93], v[152:155], v[176:179], v[90:93]
	v_mfma_f32_16x16x32_f16 v[78:81], v[144:147], v[184:187], v[78:81]
	v_mfma_f32_16x16x32_f16 v[74:77], v[152:155], v[184:187], v[74:77]
	s_setprio 0
	s_barrier
	s_add_i32 s40, 0, 0x14000
	s_add_i32 s14, s39, s26
	v_add_u32_e32 v200, s40, v137
	v_lshl_add_u64 v[204:205], s[18:19], 0, v[32:33]
	s_mov_b32 m0, s14
	ds_read_b128 v[188:191], v200
	ds_read_b128 v[192:195], v200 offset:1024
	ds_read_b128 v[196:199], v200 offset:2048
	ds_read_b128 v[200:203], v200 offset:3072
	global_load_lds_dwordx4 v[204:205], off
	v_lshl_add_u64 v[206:207], s[18:19], 0, v[130:131]
	s_add_i32 m0, s14, 0x2000
	s_nop 0
	global_load_lds_dwordx4 v[206:207], off
	s_barrier
	s_waitcnt lgkmcnt(0)
	s_setprio 1
	s_waitcnt lgkmcnt(0)
	v_mfma_f32_16x16x32_f16 v[118:121], v[188:191], v[156:159], v[118:121]
	v_mfma_f32_16x16x32_f16 v[114:117], v[196:199], v[156:159], v[114:117]
	v_mfma_f32_16x16x32_f16 v[102:105], v[188:191], v[164:167], v[102:105]
	v_mfma_f32_16x16x32_f16 v[98:101], v[196:199], v[164:167], v[98:101]
	v_mfma_f32_16x16x32_f16 v[86:89], v[188:191], v[172:175], v[86:89]
	v_mfma_f32_16x16x32_f16 v[82:85], v[196:199], v[172:175], v[82:85]
	v_mfma_f32_16x16x32_f16 v[70:73], v[188:191], v[180:183], v[70:73]
	v_mfma_f32_16x16x32_f16 v[66:69], v[196:199], v[180:183], v[66:69]
	v_mfma_f32_16x16x32_f16 v[118:121], v[192:195], v[160:163], v[118:121]
	v_mfma_f32_16x16x32_f16 v[114:117], v[200:203], v[160:163], v[114:117]
	v_mfma_f32_16x16x32_f16 v[102:105], v[192:195], v[168:171], v[102:105]
	v_mfma_f32_16x16x32_f16 v[98:101], v[200:203], v[168:171], v[98:101]
	v_mfma_f32_16x16x32_f16 v[86:89], v[192:195], v[176:179], v[86:89]
	v_mfma_f32_16x16x32_f16 v[82:85], v[200:203], v[176:179], v[82:85]
	v_mfma_f32_16x16x32_f16 v[70:73], v[192:195], v[184:187], v[70:73]
	v_mfma_f32_16x16x32_f16 v[66:69], v[200:203], v[184:187], v[66:69]
	s_setprio 0
	s_mov_b32 m0, s9
	v_lshl_add_u64 v[208:209], s[20:21], 0, v[32:33]
	s_barrier
	ds_read_b128 v[156:159], v139 offset:16384
	ds_read_b128 v[160:163], v139 offset:17408
	ds_read_b128 v[164:167], v139 offset:18432
	ds_read_b128 v[168:171], v139 offset:19456
	ds_read_b128 v[172:175], v139 offset:20480
	ds_read_b128 v[176:179], v139 offset:21504
	ds_read_b128 v[180:183], v139 offset:22528
	ds_read_b128 v[184:187], v139 offset:23552
	global_load_lds_dwordx4 v[208:209], off
	v_lshl_add_u64 v[210:211], s[20:21], 0, v[130:131]
	s_mov_b32 m0, s27
	s_nop 0
	global_load_lds_dwordx4 v[210:211], off
	s_barrier
	s_waitcnt lgkmcnt(0)
	s_setprio 1
	s_waitcnt lgkmcnt(0)
	v_mfma_f32_16x16x32_f16 v[62:65], v[140:143], v[156:159], v[62:65]
	v_mfma_f32_16x16x32_f16 v[58:61], v[148:151], v[156:159], v[58:61]
	v_mfma_f32_16x16x32_f16 v[46:49], v[140:143], v[164:167], v[46:49]
	v_mfma_f32_16x16x32_f16 v[42:45], v[148:151], v[164:167], v[42:45]
	v_mfma_f32_16x16x32_f16 v[28:31], v[140:143], v[172:175], v[28:31]
	v_mfma_f32_16x16x32_f16 v[24:27], v[148:151], v[172:175], v[24:27]
	v_mfma_f32_16x16x32_f16 v[12:15], v[140:143], v[180:183], v[12:15]
	v_mfma_f32_16x16x32_f16 v[8:11], v[148:151], v[180:183], v[8:11]
	v_mfma_f32_16x16x32_f16 v[62:65], v[144:147], v[160:163], v[62:65]
	v_mfma_f32_16x16x32_f16 v[58:61], v[152:155], v[160:163], v[58:61]
	v_mfma_f32_16x16x32_f16 v[46:49], v[144:147], v[168:171], v[46:49]
	v_mfma_f32_16x16x32_f16 v[42:45], v[152:155], v[168:171], v[42:45]
	v_mfma_f32_16x16x32_f16 v[28:31], v[144:147], v[176:179], v[28:31]
	v_mfma_f32_16x16x32_f16 v[24:27], v[152:155], v[176:179], v[24:27]
	v_mfma_f32_16x16x32_f16 v[12:15], v[144:147], v[184:187], v[12:15]
	v_mfma_f32_16x16x32_f16 v[8:11], v[152:155], v[184:187], v[8:11]
	s_setprio 0
	s_barrier
	s_add_u32 s14, s18, 0x40000
	s_addc_u32 s15, s19, 0
	s_add_i32 s39, s40, s26
	v_lshl_add_u64 v[140:141], s[14:15], 0, v[32:33]
	s_mov_b32 m0, s39
	s_nop 0
	global_load_lds_dwordx4 v[140:141], off
	v_lshl_add_u64 v[140:141], s[14:15], 0, v[130:131]
	s_add_i32 m0, s39, 0x2000
	s_nop 0
	global_load_lds_dwordx4 v[140:141], off
	s_waitcnt vmcnt(6)
	s_barrier
	s_setprio 1
	v_mfma_f32_16x16x32_f16 v[54:57], v[188:191], v[156:159], v[54:57]
	v_mfma_f32_16x16x32_f16 v[50:53], v[196:199], v[156:159], v[50:53]
	v_mfma_f32_16x16x32_f16 v[38:41], v[188:191], v[164:167], v[38:41]
	v_mfma_f32_16x16x32_f16 v[34:37], v[196:199], v[164:167], v[34:37]
	v_mfma_f32_16x16x32_f16 v[20:23], v[188:191], v[172:175], v[20:23]
	v_mfma_f32_16x16x32_f16 v[16:19], v[196:199], v[172:175], v[16:19]
	v_mfma_f32_16x16x32_f16 v[4:7], v[188:191], v[180:183], v[4:7]
	v_mfma_f32_16x16x32_f16 v[0:3], v[196:199], v[180:183], v[0:3]
	v_mfma_f32_16x16x32_f16 v[54:57], v[192:195], v[160:163], v[54:57]
	v_mfma_f32_16x16x32_f16 v[50:53], v[200:203], v[160:163], v[50:53]
	v_mfma_f32_16x16x32_f16 v[38:41], v[192:195], v[168:171], v[38:41]
	v_mfma_f32_16x16x32_f16 v[34:37], v[200:203], v[168:171], v[34:37]
	v_mfma_f32_16x16x32_f16 v[20:23], v[192:195], v[176:179], v[20:23]
	v_mfma_f32_16x16x32_f16 v[16:19], v[200:203], v[176:179], v[16:19]
	v_mfma_f32_16x16x32_f16 v[4:7], v[192:195], v[184:187], v[4:7]
	v_mfma_f32_16x16x32_f16 v[0:3], v[200:203], v[184:187], v[0:3]
	s_setprio 0
	s_add_i32 s39, 0, 0x18000
	v_add_u32_e32 v152, s39, v137
	s_barrier
	ds_read_b128 v[140:143], v152
	ds_read_b128 v[144:147], v152 offset:1024
	ds_read_b128 v[148:151], v152 offset:2048
	ds_read_b128 v[152:155], v152 offset:3072
	s_add_u32 s14, s20, 0x40000
	s_addc_u32 s15, s21, 0
	s_mov_b32 m0, s28
	v_lshl_add_u64 v[188:189], s[14:15], 0, v[32:33]
	ds_read_b128 v[156:159], v139 offset:32768
	ds_read_b128 v[160:163], v139 offset:33792
	ds_read_b128 v[164:167], v139 offset:34816
	ds_read_b128 v[168:171], v139 offset:35840
	ds_read_b128 v[172:175], v139 offset:36864
	ds_read_b128 v[176:179], v139 offset:37888
	ds_read_b128 v[180:183], v139 offset:38912
	ds_read_b128 v[184:187], v139 offset:39936
	global_load_lds_dwordx4 v[188:189], off
	v_lshl_add_u64 v[188:189], s[14:15], 0, v[130:131]
	s_mov_b32 m0, s29
	s_nop 0
	global_load_lds_dwordx4 v[188:189], off
	s_waitcnt lgkmcnt(8)
	s_barrier
	s_waitcnt lgkmcnt(0)
	s_setprio 1
	s_waitcnt lgkmcnt(0)
	v_mfma_f32_16x16x32_f16 v[126:129], v[140:143], v[156:159], v[126:129]
	v_mfma_f32_16x16x32_f16 v[122:125], v[148:151], v[156:159], v[122:125]
	v_mfma_f32_16x16x32_f16 v[110:113], v[140:143], v[164:167], v[110:113]
	v_mfma_f32_16x16x32_f16 v[106:109], v[148:151], v[164:167], v[106:109]
	v_mfma_f32_16x16x32_f16 v[94:97], v[140:143], v[172:175], v[94:97]
	v_mfma_f32_16x16x32_f16 v[90:93], v[148:151], v[172:175], v[90:93]
	v_mfma_f32_16x16x32_f16 v[78:81], v[140:143], v[180:183], v[78:81]
	v_mfma_f32_16x16x32_f16 v[74:77], v[148:151], v[180:183], v[74:77]
	v_mfma_f32_16x16x32_f16 v[126:129], v[144:147], v[160:163], v[126:129]
	v_mfma_f32_16x16x32_f16 v[122:125], v[152:155], v[160:163], v[122:125]
	v_mfma_f32_16x16x32_f16 v[110:113], v[144:147], v[168:171], v[110:113]
	v_mfma_f32_16x16x32_f16 v[106:109], v[152:155], v[168:171], v[106:109]
	v_mfma_f32_16x16x32_f16 v[94:97], v[144:147], v[176:179], v[94:97]
	v_mfma_f32_16x16x32_f16 v[90:93], v[152:155], v[176:179], v[90:93]
	v_mfma_f32_16x16x32_f16 v[78:81], v[144:147], v[184:187], v[78:81]
	v_mfma_f32_16x16x32_f16 v[74:77], v[152:155], v[184:187], v[74:77]
	s_setprio 0
	s_barrier
	s_add_i32 s20, 0, 0x1c000
	s_add_i32 s14, s39, s26
	v_add_u32_e32 v200, s20, v137
	v_lshl_add_u64 v[204:205], v[204:205], 0, s[84:85]
	s_mov_b32 m0, s14
	ds_read_b128 v[188:191], v200
	ds_read_b128 v[192:195], v200 offset:1024
	ds_read_b128 v[196:199], v200 offset:2048
	ds_read_b128 v[200:203], v200 offset:3072
	global_load_lds_dwordx4 v[204:205], off
	v_lshl_add_u64 v[204:205], v[206:207], 0, s[84:85]
	s_add_i32 m0, s14, 0x2000
	s_nop 0
	global_load_lds_dwordx4 v[204:205], off
	s_barrier
	s_waitcnt lgkmcnt(0)
	s_setprio 1
	s_waitcnt lgkmcnt(0)
	v_mfma_f32_16x16x32_f16 v[118:121], v[188:191], v[156:159], v[118:121]
	v_mfma_f32_16x16x32_f16 v[114:117], v[196:199], v[156:159], v[114:117]
	v_mfma_f32_16x16x32_f16 v[102:105], v[188:191], v[164:167], v[102:105]
	v_mfma_f32_16x16x32_f16 v[98:101], v[196:199], v[164:167], v[98:101]
	v_mfma_f32_16x16x32_f16 v[86:89], v[188:191], v[172:175], v[86:89]
	v_mfma_f32_16x16x32_f16 v[82:85], v[196:199], v[172:175], v[82:85]
	v_mfma_f32_16x16x32_f16 v[70:73], v[188:191], v[180:183], v[70:73]
	v_mfma_f32_16x16x32_f16 v[66:69], v[196:199], v[180:183], v[66:69]
	v_mfma_f32_16x16x32_f16 v[118:121], v[192:195], v[160:163], v[118:121]
	v_mfma_f32_16x16x32_f16 v[114:117], v[200:203], v[160:163], v[114:117]
	v_mfma_f32_16x16x32_f16 v[102:105], v[192:195], v[168:171], v[102:105]
	v_mfma_f32_16x16x32_f16 v[98:101], v[200:203], v[168:171], v[98:101]
	v_mfma_f32_16x16x32_f16 v[86:89], v[192:195], v[176:179], v[86:89]
	v_mfma_f32_16x16x32_f16 v[82:85], v[200:203], v[176:179], v[82:85]
	v_mfma_f32_16x16x32_f16 v[70:73], v[192:195], v[184:187], v[70:73]
	v_mfma_f32_16x16x32_f16 v[66:69], v[200:203], v[184:187], v[66:69]
	s_setprio 0
	s_mov_b32 m0, s30
	v_lshl_add_u64 v[204:205], v[208:209], 0, s[84:85]
	s_barrier
	ds_read_b128 v[156:159], v139 offset:49152
	ds_read_b128 v[160:163], v139 offset:50176
	ds_read_b128 v[164:167], v139 offset:51200
	ds_read_b128 v[168:171], v139 offset:52224
	ds_read_b128 v[172:175], v139 offset:53248
	ds_read_b128 v[176:179], v139 offset:54272
	ds_read_b128 v[180:183], v139 offset:55296
	ds_read_b128 v[184:187], v139 offset:56320
	global_load_lds_dwordx4 v[204:205], off
	v_lshl_add_u64 v[204:205], v[210:211], 0, s[84:85]
	s_mov_b32 m0, s31
	s_nop 0
	global_load_lds_dwordx4 v[204:205], off
	s_barrier
	s_waitcnt lgkmcnt(0)
	s_setprio 1
	s_waitcnt lgkmcnt(0)
	v_mfma_f32_16x16x32_f16 v[62:65], v[140:143], v[156:159], v[62:65]
	v_mfma_f32_16x16x32_f16 v[58:61], v[148:151], v[156:159], v[58:61]
	v_mfma_f32_16x16x32_f16 v[46:49], v[140:143], v[164:167], v[46:49]
	v_mfma_f32_16x16x32_f16 v[42:45], v[148:151], v[164:167], v[42:45]
	v_mfma_f32_16x16x32_f16 v[28:31], v[140:143], v[172:175], v[28:31]
	v_mfma_f32_16x16x32_f16 v[24:27], v[148:151], v[172:175], v[24:27]
	v_mfma_f32_16x16x32_f16 v[12:15], v[140:143], v[180:183], v[12:15]
	v_mfma_f32_16x16x32_f16 v[8:11], v[148:151], v[180:183], v[8:11]
	v_mfma_f32_16x16x32_f16 v[62:65], v[144:147], v[160:163], v[62:65]
	v_mfma_f32_16x16x32_f16 v[58:61], v[152:155], v[160:163], v[58:61]
	v_mfma_f32_16x16x32_f16 v[46:49], v[144:147], v[168:171], v[46:49]
	v_mfma_f32_16x16x32_f16 v[42:45], v[152:155], v[168:171], v[42:45]
	v_mfma_f32_16x16x32_f16 v[28:31], v[144:147], v[176:179], v[28:31]
	v_mfma_f32_16x16x32_f16 v[24:27], v[152:155], v[176:179], v[24:27]
	v_mfma_f32_16x16x32_f16 v[12:15], v[144:147], v[184:187], v[12:15]
	v_mfma_f32_16x16x32_f16 v[8:11], v[152:155], v[184:187], v[8:11]
	s_setprio 0
	s_barrier
	s_add_u32 s14, s18, 0x40080
	s_addc_u32 s15, s19, 0
	s_add_i32 s18, s20, s26
	v_lshl_add_u64 v[140:141], s[14:15], 0, v[32:33]
	s_mov_b32 m0, s18
	s_nop 0
	global_load_lds_dwordx4 v[140:141], off
	v_lshl_add_u64 v[140:141], s[14:15], 0, v[130:131]
	s_add_i32 m0, s18, 0x2000
	s_nop 0
	global_load_lds_dwordx4 v[140:141], off
	s_waitcnt vmcnt(6)
	s_barrier
	s_setprio 1
	v_mfma_f32_16x16x32_f16 v[54:57], v[188:191], v[156:159], v[54:57]
	v_mfma_f32_16x16x32_f16 v[50:53], v[196:199], v[156:159], v[50:53]
	v_mfma_f32_16x16x32_f16 v[38:41], v[188:191], v[164:167], v[38:41]
	v_mfma_f32_16x16x32_f16 v[34:37], v[196:199], v[164:167], v[34:37]
	v_mfma_f32_16x16x32_f16 v[20:23], v[188:191], v[172:175], v[20:23]
	v_mfma_f32_16x16x32_f16 v[16:19], v[196:199], v[172:175], v[16:19]
	v_mfma_f32_16x16x32_f16 v[4:7], v[188:191], v[180:183], v[4:7]
	v_mfma_f32_16x16x32_f16 v[0:3], v[196:199], v[180:183], v[0:3]
	v_mfma_f32_16x16x32_f16 v[54:57], v[192:195], v[160:163], v[54:57]
	v_mfma_f32_16x16x32_f16 v[50:53], v[200:203], v[160:163], v[50:53]
	v_mfma_f32_16x16x32_f16 v[38:41], v[192:195], v[168:171], v[38:41]
	v_mfma_f32_16x16x32_f16 v[34:37], v[200:203], v[168:171], v[34:37]
	v_mfma_f32_16x16x32_f16 v[20:23], v[192:195], v[176:179], v[20:23]
	v_mfma_f32_16x16x32_f16 v[16:19], v[200:203], v[176:179], v[16:19]
	v_mfma_f32_16x16x32_f16 v[4:7], v[192:195], v[184:187], v[4:7]
	v_mfma_f32_16x16x32_f16 v[0:3], v[200:203], v[184:187], v[0:3]
	s_setprio 0
	s_add_i32 s38, s38, 2
	s_add_u32 s3, s3, 0x100
	s_addc_u32 s37, s37, 0
	s_cmp_gt_u32 s38, 13
	s_mov_b64 s[14:15], s[16:17]
	s_barrier
	s_cbranch_scc0 .LBB0_1276
	v_mul_f32_e32 v144, 0xbfb8aa3b, v127
	v_mul_f32_e32 v141, 0xbfb8aa3b, v126
	v_exp_f32_e32 v145, v144
	v_mul_f32_e32 v144, 0xbfb8aa3b, v128
	v_exp_f32_e32 v141, v141
	v_exp_f32_e32 v146, v144
	v_mul_f32_e32 v144, 0xbfb8aa3b, v129
	v_exp_f32_e32 v147, v144
	v_mul_f32_e32 v144, 0xbfb8aa3b, v122
	v_exp_f32_e32 v148, v144
	v_mul_f32_e32 v144, 0xbfb8aa3b, v123
	v_exp_f32_e32 v149, v144
	v_mul_f32_e32 v144, 0xbfb8aa3b, v124
	v_exp_f32_e32 v150, v144
	v_mul_f32_e32 v144, 0xbfb8aa3b, v125
	v_add_f32_e32 v141, 1.0, v141
	v_exp_f32_e32 v151, v144
	v_rcp_f32_e32 v144, v141
	v_add_f32_e32 v141, 1.0, v145
	v_rcp_f32_e32 v145, v141
	v_add_f32_e32 v141, 1.0, v146
	v_rcp_f32_e32 v146, v141
	v_add_f32_e32 v141, 1.0, v147
	v_rcp_f32_e32 v147, v141
	v_add_f32_e32 v141, 1.0, v148
	v_rcp_f32_e32 v148, v141
	v_add_f32_e32 v141, 1.0, v149
	v_rcp_f32_e32 v149, v141
	v_add_f32_e32 v141, 1.0, v150
	v_rcp_f32_e32 v150, v141
	v_add_f32_e32 v141, 1.0, v151
	v_pk_mul_f32 v[126:127], v[126:127], v[144:145]
	v_rcp_f32_e32 v151, v141
	v_pk_mul_f32 v[118:119], v[126:127], v[118:119]
	v_pk_mul_f32 v[126:127], v[128:129], v[146:147]
	v_cvt_pk_f16_f32 v118, v118, v119
	v_pk_mul_f32 v[120:121], v[126:127], v[120:121]
	v_lshl_or_b32 v142, s36, 7, v138
	v_cvt_pk_f16_f32 v119, v120, v121
	v_pk_mul_f32 v[120:121], v[122:123], v[148:149]
	v_lshl_add_u32 v140, s8, 8, v136
	v_pk_mul_f32 v[114:115], v[120:121], v[114:115]
	v_ashrrev_i32_e32 v143, 31, v142
	v_cvt_pk_f16_f32 v120, v114, v115
	v_pk_mul_f32 v[114:115], v[124:125], v[150:151]
	s_movk_i32 s3, 0x1600
	v_pk_mul_f32 v[114:115], v[114:115], v[116:117]
	v_lshlrev_b64 v[116:117], 1, v[142:143]
	v_cvt_pk_f16_f32 v121, v114, v115
	v_mov_b64_e32 v[114:115], s[92:93]
	v_mad_i64_i32 v[122:123], s[10:11], v140, s3, v[114:115]
	v_lshl_add_u64 v[122:123], v[122:123], 0, v[116:117]
	global_store_dwordx4 v[122:123], v[118:121], off
	v_mul_f32_e32 v122, 0xbfb8aa3b, v106
	v_mul_f32_e32 v123, 0xbfb8aa3b, v107
	v_mul_f32_e32 v118, 0xbfb8aa3b, v110
	v_mul_f32_e32 v119, 0xbfb8aa3b, v111
	v_exp_f32_e32 v118, v118
	v_exp_f32_e32 v119, v119
	v_mul_f32_e32 v120, 0xbfb8aa3b, v112
	v_mul_f32_e32 v121, 0xbfb8aa3b, v113
	v_exp_f32_e32 v120, v120
	v_exp_f32_e32 v121, v121
	v_exp_f32_e32 v122, v122
	v_exp_f32_e32 v123, v123
	v_mul_f32_e32 v124, 0xbfb8aa3b, v108
	v_mul_f32_e32 v125, 0xbfb8aa3b, v109
	v_add_f32_e32 v118, 1.0, v118
	v_add_f32_e32 v119, 1.0, v119
	v_exp_f32_e32 v124, v124
	v_exp_f32_e32 v125, v125
	v_rcp_f32_e32 v118, v118
	v_rcp_f32_e32 v119, v119
	v_add_f32_e32 v120, 1.0, v120
	v_add_f32_e32 v121, 1.0, v121
	v_rcp_f32_e32 v120, v120
	v_rcp_f32_e32 v121, v121
	v_add_f32_e32 v122, 1.0, v122
	v_add_f32_e32 v123, 1.0, v123
	v_rcp_f32_e32 v122, v122
	v_rcp_f32_e32 v123, v123
	v_add_f32_e32 v124, 1.0, v124
	v_add_f32_e32 v125, 1.0, v125
	v_pk_mul_f32 v[110:111], v[110:111], v[118:119]
	v_rcp_f32_e32 v124, v124
	v_rcp_f32_e32 v125, v125
	v_pk_mul_f32 v[102:103], v[110:111], v[102:103]
	v_pk_mul_f32 v[110:111], v[112:113], v[120:121]
	v_cvt_pk_f16_f32 v102, v102, v103
	v_pk_mul_f32 v[104:105], v[110:111], v[104:105]
	s_and_b64 vcc, exec, s[0:1]
	v_cvt_pk_f16_f32 v103, v104, v105
	v_pk_mul_f32 v[104:105], v[106:107], v[122:123]
	s_mov_b32 s36, s35
	v_pk_mul_f32 v[98:99], v[104:105], v[98:99]
	s_mov_b32 s8, s2
	v_cvt_pk_f16_f32 v104, v98, v99
	v_pk_mul_f32 v[98:99], v[108:109], v[124:125]
	s_mov_b64 s[16:17], s[6:7]
	v_pk_mul_f32 v[98:99], v[98:99], v[100:101]
	v_mul_f32_e32 v100, 0xbfb8aa3b, v96
	v_cvt_pk_f16_f32 v105, v98, v99
	v_or_b32_e32 v98, 16, v140
	v_mad_i64_i32 v[98:99], s[10:11], v98, s3, v[114:115]
	v_lshl_add_u64 v[98:99], v[98:99], 0, v[116:117]
	global_store_dwordx4 v[98:99], v[102:105], off
	v_mul_f32_e32 v98, 0xbfb8aa3b, v94
	v_mul_f32_e32 v99, 0xbfb8aa3b, v95
	v_exp_f32_e32 v98, v98
	v_exp_f32_e32 v99, v99
	v_mul_f32_e32 v101, 0xbfb8aa3b, v97
	v_exp_f32_e32 v100, v100
	v_exp_f32_e32 v101, v101
	v_mul_f32_e32 v102, 0xbfb8aa3b, v90
	v_mul_f32_e32 v103, 0xbfb8aa3b, v91
	v_exp_f32_e32 v102, v102
	v_exp_f32_e32 v103, v103
	v_mul_f32_e32 v104, 0xbfb8aa3b, v92
	v_mul_f32_e32 v105, 0xbfb8aa3b, v93
	v_add_f32_e32 v98, 1.0, v98
	v_add_f32_e32 v99, 1.0, v99
	v_exp_f32_e32 v104, v104
	v_exp_f32_e32 v105, v105
	v_rcp_f32_e32 v98, v98
	v_rcp_f32_e32 v99, v99
	v_add_f32_e32 v100, 1.0, v100
	v_add_f32_e32 v101, 1.0, v101
	v_rcp_f32_e32 v100, v100
	v_rcp_f32_e32 v101, v101
	v_add_f32_e32 v102, 1.0, v102
	v_add_f32_e32 v103, 1.0, v103
	v_rcp_f32_e32 v102, v102
	v_rcp_f32_e32 v103, v103
	v_add_f32_e32 v104, 1.0, v104
	v_add_f32_e32 v105, 1.0, v105
	v_pk_mul_f32 v[94:95], v[94:95], v[98:99]
	v_rcp_f32_e32 v104, v104
	v_rcp_f32_e32 v105, v105
	v_pk_mul_f32 v[86:87], v[94:95], v[86:87]
	v_pk_mul_f32 v[94:95], v[96:97], v[100:101]
	v_cvt_pk_f16_f32 v86, v86, v87
	v_pk_mul_f32 v[88:89], v[94:95], v[88:89]
	s_mov_b64 s[14:15], s[4:5]
	v_cvt_pk_f16_f32 v87, v88, v89
	v_pk_mul_f32 v[88:89], v[90:91], v[102:103]
	s_nop 0
	v_pk_mul_f32 v[82:83], v[88:89], v[82:83]
	s_nop 0
	v_cvt_pk_f16_f32 v88, v82, v83
	v_pk_mul_f32 v[82:83], v[92:93], v[104:105]
	s_nop 0
	v_pk_mul_f32 v[82:83], v[82:83], v[84:85]
	v_mul_f32_e32 v84, 0xbfb8aa3b, v80
	v_cvt_pk_f16_f32 v89, v82, v83
	v_or_b32_e32 v82, 32, v140
	v_mad_i64_i32 v[82:83], s[10:11], v82, s3, v[114:115]
	v_lshl_add_u64 v[82:83], v[82:83], 0, v[116:117]
	global_store_dwordx4 v[82:83], v[86:89], off
	v_mul_f32_e32 v82, 0xbfb8aa3b, v78
	v_mul_f32_e32 v83, 0xbfb8aa3b, v79
	v_exp_f32_e32 v82, v82
	v_exp_f32_e32 v83, v83
	v_mul_f32_e32 v85, 0xbfb8aa3b, v81
	v_exp_f32_e32 v84, v84
	v_exp_f32_e32 v85, v85
	v_mul_f32_e32 v86, 0xbfb8aa3b, v74
	v_mul_f32_e32 v87, 0xbfb8aa3b, v75
	v_exp_f32_e32 v86, v86
	v_exp_f32_e32 v87, v87
	v_mul_f32_e32 v88, 0xbfb8aa3b, v76
	v_mul_f32_e32 v89, 0xbfb8aa3b, v77
	v_add_f32_e32 v82, 1.0, v82
	v_add_f32_e32 v83, 1.0, v83
	v_exp_f32_e32 v88, v88
	v_exp_f32_e32 v89, v89
	v_rcp_f32_e32 v82, v82
	v_rcp_f32_e32 v83, v83
	v_add_f32_e32 v84, 1.0, v84
	v_add_f32_e32 v85, 1.0, v85
	v_rcp_f32_e32 v84, v84
	v_rcp_f32_e32 v85, v85
	v_add_f32_e32 v86, 1.0, v86
	v_add_f32_e32 v87, 1.0, v87
	v_rcp_f32_e32 v86, v86
	v_rcp_f32_e32 v87, v87
	v_add_f32_e32 v88, 1.0, v88
	v_add_f32_e32 v89, 1.0, v89
	v_pk_mul_f32 v[78:79], v[78:79], v[82:83]
	v_rcp_f32_e32 v88, v88
	v_rcp_f32_e32 v89, v89
	v_pk_mul_f32 v[70:71], v[78:79], v[70:71]
	v_pk_mul_f32 v[78:79], v[80:81], v[84:85]
	v_cvt_pk_f16_f32 v70, v70, v71
	v_pk_mul_f32 v[72:73], v[78:79], v[72:73]
	s_nop 0
	v_cvt_pk_f16_f32 v71, v72, v73
	v_pk_mul_f32 v[72:73], v[74:75], v[86:87]
	v_add_u32_e32 v74, 0x80, v140
	v_pk_mul_f32 v[66:67], v[72:73], v[66:67]
	s_nop 0
	v_cvt_pk_f16_f32 v72, v66, v67
	v_pk_mul_f32 v[66:67], v[76:77], v[88:89]
	s_nop 0
	v_pk_mul_f32 v[66:67], v[66:67], v[68:69]
	v_mul_f32_e32 v68, 0xbfb8aa3b, v64
	v_cvt_pk_f16_f32 v73, v66, v67
	v_or_b32_e32 v66, 48, v140
	v_mad_i64_i32 v[66:67], s[10:11], v66, s3, v[114:115]
	v_lshl_add_u64 v[66:67], v[66:67], 0, v[116:117]
	global_store_dwordx4 v[66:67], v[70:73], off
	v_mul_f32_e32 v66, 0xbfb8aa3b, v62
	v_mul_f32_e32 v67, 0xbfb8aa3b, v63
	v_exp_f32_e32 v66, v66
	v_exp_f32_e32 v67, v67
	v_mul_f32_e32 v69, 0xbfb8aa3b, v65
	v_exp_f32_e32 v68, v68
	v_exp_f32_e32 v69, v69
	v_mul_f32_e32 v70, 0xbfb8aa3b, v58
	v_mul_f32_e32 v71, 0xbfb8aa3b, v59
	v_exp_f32_e32 v70, v70
	v_exp_f32_e32 v71, v71
	v_mul_f32_e32 v72, 0xbfb8aa3b, v60
	v_mul_f32_e32 v73, 0xbfb8aa3b, v61
	v_add_f32_e32 v66, 1.0, v66
	v_add_f32_e32 v67, 1.0, v67
	v_exp_f32_e32 v72, v72
	v_exp_f32_e32 v73, v73
	v_rcp_f32_e32 v66, v66
	v_rcp_f32_e32 v67, v67
	v_add_f32_e32 v68, 1.0, v68
	v_add_f32_e32 v69, 1.0, v69
	v_rcp_f32_e32 v68, v68
	v_rcp_f32_e32 v69, v69
	v_add_f32_e32 v70, 1.0, v70
	v_add_f32_e32 v71, 1.0, v71
	v_rcp_f32_e32 v70, v70
	v_rcp_f32_e32 v71, v71
	v_add_f32_e32 v72, 1.0, v72
	v_add_f32_e32 v73, 1.0, v73
	v_pk_mul_f32 v[62:63], v[62:63], v[66:67]
	v_rcp_f32_e32 v72, v72
	v_rcp_f32_e32 v73, v73
	v_pk_mul_f32 v[54:55], v[62:63], v[54:55]
	v_pk_mul_f32 v[62:63], v[64:65], v[68:69]
	v_cvt_pk_f16_f32 v54, v54, v55
	v_pk_mul_f32 v[56:57], v[62:63], v[56:57]
	s_nop 0
	v_cvt_pk_f16_f32 v55, v56, v57
	v_pk_mul_f32 v[56:57], v[58:59], v[70:71]
	s_nop 0
	v_pk_mul_f32 v[50:51], v[56:57], v[50:51]
	s_nop 0
	v_cvt_pk_f16_f32 v56, v50, v51
	v_pk_mul_f32 v[50:51], v[60:61], v[72:73]
	s_nop 0
	v_pk_mul_f32 v[50:51], v[50:51], v[52:53]
	v_mul_f32_e32 v52, 0xbfb8aa3b, v48
	v_cvt_pk_f16_f32 v57, v50, v51
	v_mad_i64_i32 v[50:51], s[10:11], v74, s3, v[114:115]
	v_lshl_add_u64 v[50:51], v[50:51], 0, v[116:117]
	global_store_dwordx4 v[50:51], v[54:57], off
	v_mul_f32_e32 v50, 0xbfb8aa3b, v46
	v_mul_f32_e32 v51, 0xbfb8aa3b, v47
	v_exp_f32_e32 v50, v50
	v_exp_f32_e32 v51, v51
	v_mul_f32_e32 v53, 0xbfb8aa3b, v49
	v_exp_f32_e32 v52, v52
	v_exp_f32_e32 v53, v53
	v_mul_f32_e32 v54, 0xbfb8aa3b, v42
	v_mul_f32_e32 v55, 0xbfb8aa3b, v43
	v_exp_f32_e32 v54, v54
	v_exp_f32_e32 v55, v55
	v_mul_f32_e32 v56, 0xbfb8aa3b, v44
	v_mul_f32_e32 v57, 0xbfb8aa3b, v45
	v_add_f32_e32 v50, 1.0, v50
	v_add_f32_e32 v51, 1.0, v51
	v_exp_f32_e32 v56, v56
	v_exp_f32_e32 v57, v57
	v_rcp_f32_e32 v50, v50
	v_rcp_f32_e32 v51, v51
	v_add_f32_e32 v52, 1.0, v52
	v_add_f32_e32 v53, 1.0, v53
	v_rcp_f32_e32 v52, v52
	v_rcp_f32_e32 v53, v53
	v_add_f32_e32 v54, 1.0, v54
	v_add_f32_e32 v55, 1.0, v55
	v_rcp_f32_e32 v54, v54
	v_rcp_f32_e32 v55, v55
	v_add_f32_e32 v56, 1.0, v56
	v_add_f32_e32 v57, 1.0, v57
	v_pk_mul_f32 v[46:47], v[46:47], v[50:51]
	v_rcp_f32_e32 v56, v56
	v_rcp_f32_e32 v57, v57
	v_pk_mul_f32 v[38:39], v[46:47], v[38:39]
	v_pk_mul_f32 v[46:47], v[48:49], v[52:53]
	v_cvt_pk_f16_f32 v38, v38, v39
	v_pk_mul_f32 v[40:41], v[46:47], v[40:41]
	s_nop 0
	v_cvt_pk_f16_f32 v39, v40, v41
	v_pk_mul_f32 v[40:41], v[42:43], v[54:55]
	s_nop 0
	v_pk_mul_f32 v[34:35], v[40:41], v[34:35]
	s_nop 0
	v_cvt_pk_f16_f32 v40, v34, v35
	v_pk_mul_f32 v[34:35], v[44:45], v[56:57]
	s_nop 0
	v_pk_mul_f32 v[34:35], v[34:35], v[36:37]
	v_mul_f32_e32 v36, 0xbfb8aa3b, v30
	v_cvt_pk_f16_f32 v41, v34, v35
	v_add_u32_e32 v34, 0x90, v140
	v_mad_i64_i32 v[34:35], s[10:11], v34, s3, v[114:115]
	v_lshl_add_u64 v[34:35], v[34:35], 0, v[116:117]
	global_store_dwordx4 v[34:35], v[38:41], off
	v_mul_f32_e32 v34, 0xbfb8aa3b, v28
	v_mul_f32_e32 v35, 0xbfb8aa3b, v29
	v_exp_f32_e32 v34, v34
	v_exp_f32_e32 v35, v35
	v_mul_f32_e32 v37, 0xbfb8aa3b, v31
	v_exp_f32_e32 v36, v36
	v_exp_f32_e32 v37, v37
	v_mul_f32_e32 v38, 0xbfb8aa3b, v24
	v_mul_f32_e32 v39, 0xbfb8aa3b, v25
	v_exp_f32_e32 v38, v38
	v_exp_f32_e32 v39, v39
	v_mul_f32_e32 v40, 0xbfb8aa3b, v26
	v_mul_f32_e32 v41, 0xbfb8aa3b, v27
	v_add_f32_e32 v34, 1.0, v34
	v_add_f32_e32 v35, 1.0, v35
	v_exp_f32_e32 v40, v40
	v_exp_f32_e32 v41, v41
	v_rcp_f32_e32 v34, v34
	v_rcp_f32_e32 v35, v35
	v_add_f32_e32 v36, 1.0, v36
	v_add_f32_e32 v37, 1.0, v37
	v_rcp_f32_e32 v36, v36
	v_rcp_f32_e32 v37, v37
	v_add_f32_e32 v38, 1.0, v38
	v_add_f32_e32 v39, 1.0, v39
	v_rcp_f32_e32 v38, v38
	v_rcp_f32_e32 v39, v39
	v_add_f32_e32 v40, 1.0, v40
	v_add_f32_e32 v41, 1.0, v41
	v_pk_mul_f32 v[28:29], v[28:29], v[34:35]
	v_rcp_f32_e32 v40, v40
	v_rcp_f32_e32 v41, v41
	v_pk_mul_f32 v[20:21], v[28:29], v[20:21]
	v_pk_mul_f32 v[28:29], v[30:31], v[36:37]
	v_cvt_pk_f16_f32 v20, v20, v21
	v_pk_mul_f32 v[22:23], v[28:29], v[22:23]
	s_nop 0
	v_cvt_pk_f16_f32 v21, v22, v23
	v_pk_mul_f32 v[22:23], v[24:25], v[38:39]
	s_nop 0
	v_pk_mul_f32 v[16:17], v[22:23], v[16:17]
	s_nop 0
	v_cvt_pk_f16_f32 v22, v16, v17
	v_pk_mul_f32 v[16:17], v[26:27], v[40:41]
	s_nop 0
	v_pk_mul_f32 v[16:17], v[16:17], v[18:19]
	v_mul_f32_e32 v18, 0xbfb8aa3b, v14
	v_cvt_pk_f16_f32 v23, v16, v17
	v_add_u32_e32 v16, 0xa0, v140
	v_mad_i64_i32 v[16:17], s[10:11], v16, s3, v[114:115]
	v_lshl_add_u64 v[16:17], v[16:17], 0, v[116:117]
	global_store_dwordx4 v[16:17], v[20:23], off
	v_mul_f32_e32 v16, 0xbfb8aa3b, v12
	v_mul_f32_e32 v17, 0xbfb8aa3b, v13
	v_exp_f32_e32 v16, v16
	v_exp_f32_e32 v17, v17
	v_mul_f32_e32 v19, 0xbfb8aa3b, v15
	v_exp_f32_e32 v18, v18
	v_exp_f32_e32 v19, v19
	v_mul_f32_e32 v20, 0xbfb8aa3b, v8
	v_mul_f32_e32 v21, 0xbfb8aa3b, v9
	v_exp_f32_e32 v20, v20
	v_exp_f32_e32 v21, v21
	v_mul_f32_e32 v22, 0xbfb8aa3b, v10
	v_mul_f32_e32 v23, 0xbfb8aa3b, v11
	v_add_f32_e32 v16, 1.0, v16
	v_add_f32_e32 v17, 1.0, v17
	v_exp_f32_e32 v22, v22
	v_exp_f32_e32 v23, v23
	v_rcp_f32_e32 v16, v16
	v_rcp_f32_e32 v17, v17
	v_add_f32_e32 v18, 1.0, v18
	v_add_f32_e32 v19, 1.0, v19
	v_rcp_f32_e32 v18, v18
	v_rcp_f32_e32 v19, v19
	v_add_f32_e32 v20, 1.0, v20
	v_add_f32_e32 v21, 1.0, v21
	v_rcp_f32_e32 v20, v20
	v_rcp_f32_e32 v21, v21
	v_add_f32_e32 v22, 1.0, v22
	v_add_f32_e32 v23, 1.0, v23
	v_pk_mul_f32 v[12:13], v[12:13], v[16:17]
	v_rcp_f32_e32 v22, v22
	v_rcp_f32_e32 v23, v23
	v_pk_mul_f32 v[4:5], v[12:13], v[4:5]
	v_pk_mul_f32 v[12:13], v[14:15], v[18:19]
	v_cvt_pk_f16_f32 v4, v4, v5
	v_pk_mul_f32 v[6:7], v[12:13], v[6:7]
	s_nop 0
	v_cvt_pk_f16_f32 v5, v6, v7
	v_pk_mul_f32 v[6:7], v[8:9], v[20:21]
	s_nop 0
	v_pk_mul_f32 v[0:1], v[6:7], v[0:1]
	s_nop 0
	v_cvt_pk_f16_f32 v6, v0, v1
	v_pk_mul_f32 v[0:1], v[10:11], v[22:23]
	s_nop 0
	v_pk_mul_f32 v[0:1], v[0:1], v[2:3]
	s_nop 0
	v_cvt_pk_f16_f32 v7, v0, v1
	v_add_u32_e32 v0, 0xb0, v140
	v_mad_i64_i32 v[0:1], s[10:11], v0, s3, v[114:115]
	v_lshl_add_u64 v[0:1], v[0:1], 0, v[116:117]
	global_store_dwordx4 v[0:1], v[4:7], off
	s_cmp_lg_u32 s34, 1
	s_cbranch_scc1 .Lups_skip
	s_and_b32 s0, s91, 63
	s_cmp_gt_u32 s0, 5
	s_cbranch_scc1 .Lups_skip
	s_cmp_gt_u32 s91, 196
	s_cbranch_scc1 .Lups_skip
	s_waitcnt vmcnt(0)
	s_barrier
	v_readlane_b32 s0, v251, 36
	s_cmp_lg_u32 s0, 0
	s_cbranch_scc1 .Lups_skip
	buffer_wbl2 sc1
	s_waitcnt vmcnt(0)
	v_readlane_b32 s2, v255, 45
	v_readlane_b32 s3, v254, 25
	s_lshl_b32 s2, s2, 1
	s_cmp_eq_u32 s3, 0
	s_cselect_b32 s3, 1, 0
	s_add_i32 s2, s2, s3
	s_lshl_b32 s2, s2, 2
	s_add_i32 s2, s2, 14016
	v_readlane_b32 s0, v251, 32
	v_readlane_b32 s1, v251, 33
	s_add_u32 s0, s0, s2
	s_addc_u32 s1, s1, 0
	s_mov_b64 s[2:3], exec
	s_mov_b64 exec, 1
	global_atomic_add v33, v248, s[0:1]
	s_mov_b64 exec, s[2:3]
.Lups_skip:
	s_cbranch_vccz .LBB0_1269
	s_waitcnt vmcnt(0)
	s_cmpk_gt_u32 s23, 0xff
	s_cbranch_scc1 .LBB0_1280
	s_barrier
.LBB0_1280:
	v_readlane_b32 s4, v252, 47
	v_readlane_b32 s5, v252, 48
	s_barrier
	s_sub_i32 s0, s91, 150
	s_cmp_gt_u32 s0, 43
	s_cbranch_scc1 .Ldnc_skip
	v_readlane_b32 s1, v253, 15
	v_readlane_b32 s2, v254, 25
	s_or_b32 s1, s1, s2
	s_cmp_eq_u32 s1, 0
	s_cbranch_scc1 .Ldnc_skip
	s_addk_i32 s0, 0x100
	v_writelane_b32 v255, s0, 47
	v_readlane_b32 s4, v251, 36
	s_cmp_lg_u32 s4, 0
	s_cbranch_scc1 .Ldnc_wait
	v_readlane_b32 s12, v255, 45
	v_readlane_b32 s13, v254, 25
	s_lshl_b32 s12, s12, 1
	s_cmp_eq_u32 s13, 0
	s_cselect_b32 s13, 1, 0
	s_add_i32 s12, s12, s13
	s_lshl_b32 s12, s12, 2
	s_add_i32 s12, s12, 14016
	v_readlane_b32 s4, v251, 32
	v_readlane_b32 s5, v251, 33
	s_add_u32 s4, s4, s12
	s_addc_u32 s5, s5, 0
	s_mov_b32 s1, 0
	v_mov_b32_e32 v0, 0
.Ldnc_poll:
	global_load_dword v1, v0, s[4:5] sc1
	s_waitcnt vmcnt(0)
	v_readfirstlane_b32 s2, v1
	s_cmp_ge_u32 s2, 23
	s_cbranch_scc1 .Ldnc_wait
	s_sleep 4
	s_add_i32 s1, s1, 1
	s_cmp_lt_u32 s1, 20000
	s_cbranch_scc1 .Ldnc_poll
.Ldnc_wait:
	s_barrier
	buffer_inv sc1
	s_waitcnt vmcnt(0)
	s_branch .LBB0_1338
.Ldnc_resume:
.Ldnc_skip:
	v_readlane_b32 s3, v252, 46
	v_readlane_b32 s12, v255, 45
	s_cmp_lt_u32 s3, 194
	s_cbranch_scc1 .Lcvtg_skip
	s_cmp_gt_u32 s12, 2
	s_cbranch_scc1 .Lcvtg_skip
	s_add_i32 s12, s12, 1
	v_readlane_b32 s4, v251, 36
	v_readlane_b32 s5, v254, 25
	s_sub_i32 s0, s3, 194
	s_lshl_b32 s0, s0, 3
	s_add_i32 s0, s0, s4
	s_mul_i32 s15, s4, 0x2100
	s_mov_b32 s1, 496
	s_cmp_lg_u32 s5, 0
	s_movk_i32 s14, 14336
	s_cselect_b32 s14, 3760, s14
	s_cselect_b32 s3, 0, 10576
	s_add_i32 s0, s0, s3

.LBB0_1338:
	v_readlane_b32 s18, v255, 47
	s_cmp_eq_u32 s18, 0
	s_cselect_b32 s18, s91, s18
	v_readlane_b32 s0, v253, 15
	v_readlane_b32 s2, v254, 25
	v_readlane_b32 s1, v253, 16
	v_readlane_b32 s3, v254, 26
	s_or_b64 s[0:1], s[0:1], s[2:3]
	s_and_b64 s[0:1], s[0:1], exec
	v_readlane_b32 s2, v251, 36
	s_movk_i32 s0, 0x12c
	s_waitcnt vmcnt(0)
	v_lshl_add_u32 v8, s2, 6, v220
	s_movk_i32 s20, 0x100
	s_cmp_lt_u32 s18, 0x100
	s_cbranch_scc1 .Ldne_n
	s_add_i32 s20, s18, 1
.Ldne_n:
	s_cmp_ge_i32 s18, s20
	v_readfirstlane_b32 s19, v8
	s_cbranch_scc0 .LBB0_1339
	s_getpc_b64 s[98:99]

.LBB0_1369:
	s_waitcnt vmcnt(0)
	v_readlane_b32 s0, v255, 47
	s_cmp_eq_u32 s0, 0
	s_cbranch_scc1 .Ldnx_normal
	s_cmpk_gt_u32 s19, 0xff
	s_cbranch_scc1 .Ldnx_a
	s_barrier
.Ldnx_a:
	s_barrier
	s_mov_b32 s0, 0
	v_writelane_b32 v255, s0, 47
	s_branch .Ldnc_resume
.Ldnx_normal:
	s_cmpk_gt_u32 s19, 0xff
	s_cbranch_scc0 .LBB0_1370
	s_getpc_b64 s[98:99]
